# ProjGate peeled first iteration: its two LDS-DMA waits now leave all 16 (minimum) stores of the previous epilogue in flight (vmcnt 24 instead of 16)
# speedup vs baseline: 1.0031x; 1.0031x over previous
; #define PG8_STAGE(bufoff, gbase, voff) do { _Pragma("unroll") for (int _i = 0; _i < 2; ++_i) \
;         __builtin_amdgcn_global_load_lds((const unsigned*)((const char*)(gbase) + (voff)[_i]), (PG8_LAS unsigned*)(lds + (bufoff) + ldsw + _i * 8192), 16, 0, 0); } while (0)
; #define PG8_LDA(dst, b, h) do { _Pragma("unroll") for (int m = 0; m < 4; ++m) _Pragma("unroll") for (int k = 0; k < 2; ++k) dst[m][k] = *(const PG8_LAS bf16x8*)(lds + PG8_SA(b, h) + aoff + m * 2048 + k * 1024); } while (0)
; #define PG8_LDB(dst, b, h) do { _Pragma("unroll") for (int n = 0; n < 2; ++n) _Pragma("unroll") for (int k = 0; k < 2; ++k) dst[n][k] = *(const PG8_LAS bf16x8*)(lds + PG8_SB(b, h) + boff + n * 2048 + k * 1024); } while (0)
; #define PG8_MMA(ai, bj, At, Bt) do { __builtin_amdgcn_s_setprio(1); _Pragma("unroll") for (int m = 0; m < 4; ++m) _Pragma("unroll") for (int n = 0; n < 2; ++n) _Pragma("unroll") for (int k = 0; k < 2; ++k) \
;         acc[ai][bj][m][n] = __builtin_amdgcn_mfma_f32_16x16x32_bf16(Bt[n][k], At[m][k], acc[ai][bj][m][n], 0, 0, 0); __builtin_amdgcn_s_setprio(0); } while (0)
; #define PG8_WAIT_V(n) asm volatile("s_waitcnt vmcnt(" #n ")" ::: "memory")
; #define PG8_WAIT_L(n) asm volatile("s_waitcnt lgkmcnt(" #n ")" ::: "memory")
; #define PG8_BAR __builtin_amdgcn_s_barrier()
; #define PG8_SCHED __builtin_amdgcn_sched_barrier(0)
; template <class Epi, class Sched, bool ALIGN_EPI = false, bool SP2 = false>
; __device__ __forceinline__ void gemm_phase(PG8_LAS unsigned char* lds, const Gemm g, const Sched& S, const Epi& E) {
;     ...
;             PG8_LDB(B0, 0, 0); PG8_LDB(B1, 0, 1); PG8_SCHED; PG8_LDA(At, 0, 0); PG8_STAGE(PG8_SA(1, 1), a1 + hstep, voffA);
;             PG8_WAIT_V(8); PG8_WAIT_L(0); PG8_BAR; PG8_MMA(0, 0, At, B0); PG8_MMA(0, 1, At, B1); PG8_BAR; PG8_SCHED;
;             PG8_LDA(At, 0, 1); PG8_STAGE(PG8_SB(0, 0), b2, voffB); PG8_STAGE(PG8_SB(0, 1), b2 + hstep, voffB); PG8_STAGE(PG8_SA(0, 0), a2, voffA);
;             PG8_WAIT_V(8); PG8_WAIT_L(0); PG8_BAR; PG8_MMA(1, 0, At, B0); PG8_MMA(1, 1, At, B1); PG8_BAR; PG8_SCHED;
.Lpeel_pg:
	s_add_u32 s4, s0, 0xfffc0080
	s_addc_u32 s5, s1, -1
	s_add_i32 s60, 0, 0x10000
	s_cmp_eq_u32 s59, 12
	s_cselect_b32 s43, s21, s5
	s_cselect_b32 s42, s45, s4
	s_cselect_b32 s5, s19, s58
	s_cselect_b32 s4, s46, s47
	s_add_i32 s62, 0, 0x14000
	v_add_u32_e32 v144, s60, v170
	v_add_u32_e32 v174, s62, v170
	ds_read_b128 v[132:135], v144
	ds_read_b128 v[136:139], v144 offset:1024
	ds_read_b128 v[140:143], v144 offset:2048
	ds_read_b128 v[144:147], v144 offset:3072
	ds_read_b128 v[158:161], v174
	ds_read_b128 v[162:165], v174 offset:1024
	ds_read_b128 v[166:169], v174 offset:2048
	ds_read_b128 v[174:177], v174 offset:3072
	v_lshl_add_u64 v[194:195], s[0:1], 0, v[154:155]
	s_add_i32 m0, s50, 0xc000
	ds_read_b128 v[178:181], v173
	ds_read_b128 v[182:185], v173 offset:1024
	ds_read_b128 v[186:189], v173 offset:2048
	ds_read_b128 v[190:193], v173 offset:3072
	ds_read_b128 v[202:205], v173 offset:4096
	ds_read_b128 v[206:209], v173 offset:5120
	ds_read_b128 v[210:213], v173 offset:6144
	ds_read_b128 v[214:217], v173 offset:7168
	global_load_lds_dwordx4 v[194:195], off
	v_lshl_add_u64 v[194:195], s[0:1], 0, v[156:157]
	s_add_i32 m0, s50, 0xe000
	s_nop 0
	global_load_lds_dwordx4 v[194:195], off
	s_waitcnt vmcnt(24)
	s_waitcnt lgkmcnt(0)
	v_mfma_f32_16x16x32_bf16 v[128:131], v[132:135], v[178:181], 0
	v_mfma_f32_16x16x32_bf16 v[124:127], v[140:143], v[178:181], 0
	v_mfma_f32_16x16x32_bf16 v[112:115], v[132:135], v[186:189], 0
	v_mfma_f32_16x16x32_bf16 v[108:111], v[140:143], v[186:189], 0
	s_barrier
	s_setprio 1
	v_mfma_f32_16x16x32_bf16 v[96:99], v[132:135], v[202:205], 0
	v_mfma_f32_16x16x32_bf16 v[92:95], v[140:143], v[202:205], 0
	v_mfma_f32_16x16x32_bf16 v[80:83], v[132:135], v[210:213], 0
	v_mfma_f32_16x16x32_bf16 v[76:79], v[140:143], v[210:213], 0
	v_mfma_f32_16x16x32_bf16 v[128:131], v[136:139], v[182:185], v[128:131]
	v_mfma_f32_16x16x32_bf16 v[124:127], v[144:147], v[182:185], v[124:127]
	v_mfma_f32_16x16x32_bf16 v[112:115], v[136:139], v[190:193], v[112:115]
	v_mfma_f32_16x16x32_bf16 v[108:111], v[144:147], v[190:193], v[108:111]
	v_mfma_f32_16x16x32_bf16 v[96:99], v[136:139], v[206:209], v[96:99]
	v_mfma_f32_16x16x32_bf16 v[92:95], v[144:147], v[206:209], v[92:95]
	v_mfma_f32_16x16x32_bf16 v[80:83], v[136:139], v[214:217], v[80:83]
	v_mfma_f32_16x16x32_bf16 v[76:79], v[144:147], v[214:217], v[76:79]
	s_setprio 0
	s_setprio 1
	v_mfma_f32_16x16x32_bf16 v[120:123], v[158:161], v[178:181], 0
	v_mfma_f32_16x16x32_bf16 v[116:119], v[166:169], v[178:181], 0
	v_mfma_f32_16x16x32_bf16 v[104:107], v[158:161], v[186:189], 0
	v_mfma_f32_16x16x32_bf16 v[100:103], v[166:169], v[186:189], 0
	v_mfma_f32_16x16x32_bf16 v[88:91], v[158:161], v[202:205], 0
	v_mfma_f32_16x16x32_bf16 v[84:87], v[166:169], v[202:205], 0
	v_mfma_f32_16x16x32_bf16 v[72:75], v[158:161], v[210:213], 0
	v_mfma_f32_16x16x32_bf16 v[68:71], v[166:169], v[210:213], 0
	v_mfma_f32_16x16x32_bf16 v[120:123], v[162:165], v[182:185], v[120:123]
	v_mfma_f32_16x16x32_bf16 v[116:119], v[174:177], v[182:185], v[116:119]
	v_mfma_f32_16x16x32_bf16 v[104:107], v[162:165], v[190:193], v[104:107]
	v_mfma_f32_16x16x32_bf16 v[100:103], v[174:177], v[190:193], v[100:103]
	v_mfma_f32_16x16x32_bf16 v[88:91], v[162:165], v[206:209], v[88:91]
	v_mfma_f32_16x16x32_bf16 v[84:87], v[174:177], v[206:209], v[84:87]
	v_mfma_f32_16x16x32_bf16 v[72:75], v[162:165], v[214:217], v[72:75]
	v_mfma_f32_16x16x32_bf16 v[68:71], v[174:177], v[214:217], v[68:71]
	s_setprio 0
	s_barrier
	s_add_i32 s60, s60, s49
	v_lshl_add_u64 v[194:195], s[4:5], 0, v[150:151]
	s_mov_b32 m0, s60
	ds_read_b128 v[178:181], v173 offset:16384
	ds_read_b128 v[182:185], v173 offset:17408
	ds_read_b128 v[186:189], v173 offset:18432
	ds_read_b128 v[190:193], v173 offset:19456
	ds_read_b128 v[202:205], v173 offset:20480
	ds_read_b128 v[206:209], v173 offset:21504
	ds_read_b128 v[210:213], v173 offset:22528
	ds_read_b128 v[214:217], v173 offset:23552
	global_load_lds_dwordx4 v[194:195], off
	s_add_i32 m0, s60, 0x2000
	s_add_u32 s60, s4, 0x40000
	v_lshl_add_u64 v[218:219], s[4:5], 0, v[32:33]
	s_addc_u32 s61, s5, 0
	s_add_i32 s62, s62, s49
	global_load_lds_dwordx4 v[218:219], off
	v_lshl_add_u64 v[220:221], s[60:61], 0, v[150:151]
	s_mov_b32 m0, s62
	v_lshl_add_u64 v[222:223], s[42:43], 0, v[148:149]
	global_load_lds_dwordx4 v[220:221], off
	v_lshl_add_u64 v[220:221], s[60:61], 0, v[32:33]
	s_add_i32 m0, s62, 0x2000
	s_nop 0
	global_load_lds_dwordx4 v[220:221], off
	v_lshl_add_u64 v[220:221], s[42:43], 0, v[152:153]
	s_mov_b32 m0, s50
	s_nop 0
	global_load_lds_dwordx4 v[220:221], off
	s_mov_b32 m0, s51
	s_nop 0
	global_load_lds_dwordx4 v[222:223], off
	s_waitcnt vmcnt(24)
	s_waitcnt lgkmcnt(0)
	v_mfma_f32_16x16x32_bf16 v[64:67], v[132:135], v[178:181], 0
	v_mfma_f32_16x16x32_bf16 v[60:63], v[140:143], v[178:181], 0
	v_mfma_f32_16x16x32_bf16 v[48:51], v[132:135], v[186:189], 0
	v_mfma_f32_16x16x32_bf16 v[44:47], v[140:143], v[186:189], 0
	s_barrier
; #define PG8_STAGE(bufoff, gbase, voff) do { _Pragma("unroll") for (int _i = 0; _i < 2; ++_i) \
;         __builtin_amdgcn_global_load_lds((const unsigned*)((const char*)(gbase) + (voff)[_i]), (PG8_LAS unsigned*)(lds + (bufoff) + ldsw + _i * 8192), 16, 0, 0); } while (0)
; #define PG8_LDA(dst, b, h) do { _Pragma("unroll") for (int m = 0; m < 4; ++m) _Pragma("unroll") for (int k = 0; k < 2; ++k) dst[m][k] = *(const PG8_LAS bf16x8*)(lds + PG8_SA(b, h) + aoff + m * 2048 + k * 1024); } while (0)
; #define PG8_LDB(dst, b, h) do { _Pragma("unroll") for (int n = 0; n < 2; ++n) _Pragma("unroll") for (int k = 0; k < 2; ++k) dst[n][k] = *(const PG8_LAS bf16x8*)(lds + PG8_SB(b, h) + boff + n * 2048 + k * 1024); } while (0)
; #define PG8_MMA(ai, bj, At, Bt) do { __builtin_amdgcn_s_setprio(1); _Pragma("unroll") for (int m = 0; m < 4; ++m) _Pragma("unroll") for (int n = 0; n < 2; ++n) _Pragma("unroll") for (int k = 0; k < 2; ++k) \
;         acc[ai][bj][m][n] = __builtin_amdgcn_mfma_f32_16x16x32_bf16(Bt[n][k], At[m][k], acc[ai][bj][m][n], 0, 0, 0); __builtin_amdgcn_s_setprio(0); } while (0)
; #define PG8_WAIT_V(n) asm volatile("s_waitcnt vmcnt(" #n ")" ::: "memory")
; #define PG8_WAIT_L(n) asm volatile("s_waitcnt lgkmcnt(" #n ")" ::: "memory")
; #define PG8_BAR __builtin_amdgcn_s_barrier()
; #define PG8_SCHED __builtin_amdgcn_sched_barrier(0)
; template <class Epi, class Sched, bool ALIGN_EPI = false, bool SP2 = false>
; __device__ __forceinline__ void gemm_phase(PG8_LAS unsigned char* lds, const Gemm g, const Sched& S, const Epi& E) {
;     ...
;             PG8_WAIT_V(8); PG8_WAIT_L(0); PG8_BAR; PG8_MMA(1, 0, At, B0); PG8_MMA(1, 1, At, B1); PG8_BAR; PG8_SCHED;
;             PG8_LDB(B0, 1, 0); PG8_LDB(B1, 1, 1); PG8_SCHED; PG8_LDA(At, 1, 0); PG8_STAGE(PG8_SA(0, 1), a2 + hstep, voffA);
;             PG8_WAIT_V(8); PG8_WAIT_L(0); PG8_BAR; PG8_MMA(0, 0, At, B0); PG8_MMA(0, 1, At, B1); PG8_BAR; PG8_SCHED;
	s_setprio 1
	v_mfma_f32_16x16x32_bf16 v[28:31], v[132:135], v[202:205], 0
	v_mfma_f32_16x16x32_bf16 v[24:27], v[140:143], v[202:205], 0
	v_mfma_f32_16x16x32_bf16 v[12:15], v[132:135], v[210:213], 0
	v_mfma_f32_16x16x32_bf16 v[8:11], v[140:143], v[210:213], 0
	v_mfma_f32_16x16x32_bf16 v[64:67], v[136:139], v[182:185], v[64:67]
	v_mfma_f32_16x16x32_bf16 v[60:63], v[144:147], v[182:185], v[60:63]
	v_mfma_f32_16x16x32_bf16 v[48:51], v[136:139], v[190:193], v[48:51]
	v_mfma_f32_16x16x32_bf16 v[44:47], v[144:147], v[190:193], v[44:47]
	v_mfma_f32_16x16x32_bf16 v[28:31], v[136:139], v[206:209], v[28:31]
	v_mfma_f32_16x16x32_bf16 v[24:27], v[144:147], v[206:209], v[24:27]
	v_mfma_f32_16x16x32_bf16 v[12:15], v[136:139], v[214:217], v[12:15]
	v_mfma_f32_16x16x32_bf16 v[8:11], v[144:147], v[214:217], v[8:11]
	s_setprio 0
	s_setprio 1
	v_mfma_f32_16x16x32_bf16 v[56:59], v[158:161], v[178:181], 0
	v_mfma_f32_16x16x32_bf16 v[52:55], v[166:169], v[178:181], 0
	v_mfma_f32_16x16x32_bf16 v[40:43], v[158:161], v[186:189], 0
	v_mfma_f32_16x16x32_bf16 v[36:39], v[166:169], v[186:189], 0
	v_mfma_f32_16x16x32_bf16 v[20:23], v[158:161], v[202:205], 0
	v_mfma_f32_16x16x32_bf16 v[16:19], v[166:169], v[202:205], 0
	v_mfma_f32_16x16x32_bf16 v[4:7], v[158:161], v[210:213], 0
	v_mfma_f32_16x16x32_bf16 v[0:3], v[166:169], v[210:213], 0
	v_mfma_f32_16x16x32_bf16 v[56:59], v[162:165], v[182:185], v[56:59]
	v_mfma_f32_16x16x32_bf16 v[52:55], v[174:177], v[182:185], v[52:55]
	v_mfma_f32_16x16x32_bf16 v[40:43], v[162:165], v[190:193], v[40:43]
	v_mfma_f32_16x16x32_bf16 v[36:39], v[174:177], v[190:193], v[36:39]
	v_mfma_f32_16x16x32_bf16 v[20:23], v[162:165], v[206:209], v[20:23]
	v_mfma_f32_16x16x32_bf16 v[16:19], v[174:177], v[206:209], v[16:19]
	v_mfma_f32_16x16x32_bf16 v[4:7], v[162:165], v[214:217], v[4:7]
	v_mfma_f32_16x16x32_bf16 v[0:3], v[174:177], v[214:217], v[0:3]
	s_setprio 0
	s_barrier
	s_add_i32 s60, 0, 0x18000
	s_add_i32 s61, 0, 0x1c000
	v_add_u32_e32 v144, s60, v170
	v_add_u32_e32 v174, s61, v170
	ds_read_b128 v[132:135], v144
	ds_read_b128 v[136:139], v144 offset:1024
	ds_read_b128 v[140:143], v144 offset:2048
	ds_read_b128 v[144:147], v144 offset:3072
	ds_read_b128 v[158:161], v174
	ds_read_b128 v[162:165], v174 offset:1024
	ds_read_b128 v[166:169], v174 offset:2048
	ds_read_b128 v[174:177], v174 offset:3072
	s_add_u32 s42, s42, 0x40000
	s_addc_u32 s43, s43, 0
	s_mov_b32 m0, s52
	v_lshl_add_u64 v[224:225], s[42:43], 0, v[152:153]
	ds_read_b128 v[178:181], v173 offset:32768
	ds_read_b128 v[182:185], v173 offset:33792
	ds_read_b128 v[186:189], v173 offset:34816
	ds_read_b128 v[190:193], v173 offset:35840
	ds_read_b128 v[202:205], v173 offset:36864
	ds_read_b128 v[206:209], v173 offset:37888
	ds_read_b128 v[210:213], v173 offset:38912
	ds_read_b128 v[214:217], v173 offset:39936
	global_load_lds_dwordx4 v[224:225], off
	v_lshl_add_u64 v[224:225], s[42:43], 0, v[148:149]
	s_mov_b32 m0, s53
	s_nop 0
	global_load_lds_dwordx4 v[224:225], off
	s_waitcnt vmcnt(8)
	s_waitcnt lgkmcnt(0)
	v_mfma_f32_16x16x32_bf16 v[128:131], v[132:135], v[178:181], v[128:131]
	v_mfma_f32_16x16x32_bf16 v[124:127], v[140:143], v[178:181], v[124:127]
	v_mfma_f32_16x16x32_bf16 v[112:115], v[132:135], v[186:189], v[112:115]
	v_mfma_f32_16x16x32_bf16 v[108:111], v[140:143], v[186:189], v[108:111]
	s_barrier
	s_setprio 1
	v_mfma_f32_16x16x32_bf16 v[96:99], v[132:135], v[202:205], v[96:99]
	v_mfma_f32_16x16x32_bf16 v[92:95], v[140:143], v[202:205], v[92:95]
	v_mfma_f32_16x16x32_bf16 v[80:83], v[132:135], v[210:213], v[80:83]
	v_mfma_f32_16x16x32_bf16 v[76:79], v[140:143], v[210:213], v[76:79]
	v_mfma_f32_16x16x32_bf16 v[128:131], v[136:139], v[182:185], v[128:131]
	v_mfma_f32_16x16x32_bf16 v[124:127], v[144:147], v[182:185], v[124:127]
	v_mfma_f32_16x16x32_bf16 v[112:115], v[136:139], v[190:193], v[112:115]
	v_mfma_f32_16x16x32_bf16 v[108:111], v[144:147], v[190:193], v[108:111]
	v_mfma_f32_16x16x32_bf16 v[96:99], v[136:139], v[206:209], v[96:99]
	v_mfma_f32_16x16x32_bf16 v[92:95], v[144:147], v[206:209], v[92:95]
	v_mfma_f32_16x16x32_bf16 v[80:83], v[136:139], v[214:217], v[80:83]
	v_mfma_f32_16x16x32_bf16 v[76:79], v[144:147], v[214:217], v[76:79]
	s_setprio 0
	s_setprio 1
	v_mfma_f32_16x16x32_bf16 v[120:123], v[158:161], v[178:181], v[120:123]
	v_mfma_f32_16x16x32_bf16 v[116:119], v[166:169], v[178:181], v[116:119]
	v_mfma_f32_16x16x32_bf16 v[104:107], v[158:161], v[186:189], v[104:107]
	v_mfma_f32_16x16x32_bf16 v[100:103], v[166:169], v[186:189], v[100:103]
	v_mfma_f32_16x16x32_bf16 v[88:91], v[158:161], v[202:205], v[88:91]
	v_mfma_f32_16x16x32_bf16 v[84:87], v[166:169], v[202:205], v[84:87]
	v_mfma_f32_16x16x32_bf16 v[72:75], v[158:161], v[210:213], v[72:75]
	v_mfma_f32_16x16x32_bf16 v[68:71], v[166:169], v[210:213], v[68:71]
	v_mfma_f32_16x16x32_bf16 v[120:123], v[162:165], v[182:185], v[120:123]
	v_mfma_f32_16x16x32_bf16 v[116:119], v[174:177], v[182:185], v[116:119]
	v_mfma_f32_16x16x32_bf16 v[104:107], v[162:165], v[190:193], v[104:107]
	v_mfma_f32_16x16x32_bf16 v[100:103], v[174:177], v[190:193], v[100:103]
	v_mfma_f32_16x16x32_bf16 v[88:91], v[162:165], v[206:209], v[88:91]
	v_mfma_f32_16x16x32_bf16 v[84:87], v[174:177], v[206:209], v[84:87]
	v_mfma_f32_16x16x32_bf16 v[72:75], v[162:165], v[214:217], v[72:75]
	v_mfma_f32_16x16x32_bf16 v[68:71], v[174:177], v[214:217], v[68:71]
	s_setprio 0
	s_barrier
; #define PG8_STAGE(bufoff, gbase, voff) do { _Pragma("unroll") for (int _i = 0; _i < 2; ++_i) \
;         __builtin_amdgcn_global_load_lds((const unsigned*)((const char*)(gbase) + (voff)[_i]), (PG8_LAS unsigned*)(lds + (bufoff) + ldsw + _i * 8192), 16, 0, 0); } while (0)
; #define PG8_LDA(dst, b, h) do { _Pragma("unroll") for (int m = 0; m < 4; ++m) _Pragma("unroll") for (int k = 0; k < 2; ++k) dst[m][k] = *(const PG8_LAS bf16x8*)(lds + PG8_SA(b, h) + aoff + m * 2048 + k * 1024); } while (0)
; #define PG8_MMA(ai, bj, At, Bt) do { __builtin_amdgcn_s_setprio(1); _Pragma("unroll") for (int m = 0; m < 4; ++m) _Pragma("unroll") for (int n = 0; n < 2; ++n) _Pragma("unroll") for (int k = 0; k < 2; ++k) \
;         acc[ai][bj][m][n] = __builtin_amdgcn_mfma_f32_16x16x32_bf16(Bt[n][k], At[m][k], acc[ai][bj][m][n], 0, 0, 0); __builtin_amdgcn_s_setprio(0); } while (0)
; #define PG8_WAIT_V(n) asm volatile("s_waitcnt vmcnt(" #n ")" ::: "memory")
; #define PG8_WAIT_L(n) asm volatile("s_waitcnt lgkmcnt(" #n ")" ::: "memory")
; #define PG8_BAR __builtin_amdgcn_s_barrier()
; #define PG8_SCHED __builtin_amdgcn_sched_barrier(0)
; template <class Epi, class Sched, bool ALIGN_EPI = false, bool SP2 = false>
; __device__ __forceinline__ void gemm_phase(PG8_LAS unsigned char* lds, const Gemm g, const Sched& S, const Epi& E) {
;     ...
;             PG8_LDA(At, 1, 1); PG8_STAGE(PG8_SB(1, 0), b3, voffB); PG8_STAGE(PG8_SB(1, 1), b3 + hstep, voffB); PG8_STAGE(PG8_SA(1, 0), a3, voffA);
;             PG8_WAIT_V(8); PG8_WAIT_L(0); PG8_BAR; PG8_MMA(1, 0, At, B0); PG8_MMA(1, 1, At, B1); PG8_BAR; PG8_SCHED;
	s_add_i32 s42, s60, s49
	v_lshl_add_u64 v[194:195], v[194:195], 0, s[36:37]
	s_mov_b32 m0, s42
	ds_read_b128 v[178:181], v173 offset:49152
	ds_read_b128 v[182:185], v173 offset:50176
	ds_read_b128 v[186:189], v173 offset:51200
	ds_read_b128 v[190:193], v173 offset:52224
	ds_read_b128 v[202:205], v173 offset:53248
	ds_read_b128 v[206:209], v173 offset:54272
	ds_read_b128 v[210:213], v173 offset:55296
	ds_read_b128 v[214:217], v173 offset:56320
	global_load_lds_dwordx4 v[194:195], off
	s_add_i32 m0, s42, 0x2000
	s_add_u32 s4, s4, 0x40080
	v_lshl_add_u64 v[194:195], v[218:219], 0, s[36:37]
	s_addc_u32 s5, s5, 0
	s_add_i32 s42, s61, s49
	global_load_lds_dwordx4 v[194:195], off
	v_lshl_add_u64 v[194:195], s[4:5], 0, v[150:151]
	s_mov_b32 m0, s42
	s_nop 0
	global_load_lds_dwordx4 v[194:195], off
	v_lshl_add_u64 v[194:195], s[4:5], 0, v[32:33]
	s_add_i32 m0, s42, 0x2000
	s_nop 0
	global_load_lds_dwordx4 v[194:195], off
	v_lshl_add_u64 v[194:195], v[220:221], 0, s[36:37]
	s_mov_b32 m0, s54
	s_nop 0
	global_load_lds_dwordx4 v[194:195], off
	v_lshl_add_u64 v[194:195], v[222:223], 0, s[36:37]
	s_mov_b32 m0, s55
	s_nop 0
	global_load_lds_dwordx4 v[194:195], off
	s_waitcnt vmcnt(8)
	s_waitcnt lgkmcnt(0)
	v_mfma_f32_16x16x32_bf16 v[64:67], v[132:135], v[178:181], v[64:67]
	v_mfma_f32_16x16x32_bf16 v[60:63], v[140:143], v[178:181], v[60:63]
	v_mfma_f32_16x16x32_bf16 v[48:51], v[132:135], v[186:189], v[48:51]
	v_mfma_f32_16x16x32_bf16 v[44:47], v[140:143], v[186:189], v[44:47]
	s_barrier
	s_setprio 1
	v_mfma_f32_16x16x32_bf16 v[28:31], v[132:135], v[202:205], v[28:31]
	v_mfma_f32_16x16x32_bf16 v[24:27], v[140:143], v[202:205], v[24:27]
	v_mfma_f32_16x16x32_bf16 v[12:15], v[132:135], v[210:213], v[12:15]
	v_mfma_f32_16x16x32_bf16 v[8:11], v[140:143], v[210:213], v[8:11]
	v_mfma_f32_16x16x32_bf16 v[64:67], v[136:139], v[182:185], v[64:67]
	v_mfma_f32_16x16x32_bf16 v[60:63], v[144:147], v[182:185], v[60:63]
	v_mfma_f32_16x16x32_bf16 v[48:51], v[136:139], v[190:193], v[48:51]
	v_mfma_f32_16x16x32_bf16 v[44:47], v[144:147], v[190:193], v[44:47]
	v_mfma_f32_16x16x32_bf16 v[28:31], v[136:139], v[206:209], v[28:31]
	v_mfma_f32_16x16x32_bf16 v[24:27], v[144:147], v[206:209], v[24:27]
	v_mfma_f32_16x16x32_bf16 v[12:15], v[136:139], v[214:217], v[12:15]
	v_mfma_f32_16x16x32_bf16 v[8:11], v[144:147], v[214:217], v[8:11]
	s_setprio 0
	s_setprio 1
	v_mfma_f32_16x16x32_bf16 v[56:59], v[158:161], v[178:181], v[56:59]
	v_mfma_f32_16x16x32_bf16 v[52:55], v[166:169], v[178:181], v[52:55]
	v_mfma_f32_16x16x32_bf16 v[40:43], v[158:161], v[186:189], v[40:43]
	v_mfma_f32_16x16x32_bf16 v[36:39], v[166:169], v[186:189], v[36:39]
	v_mfma_f32_16x16x32_bf16 v[20:23], v[158:161], v[202:205], v[20:23]
	v_mfma_f32_16x16x32_bf16 v[16:19], v[166:169], v[202:205], v[16:19]
	v_mfma_f32_16x16x32_bf16 v[4:7], v[158:161], v[210:213], v[4:7]
	v_mfma_f32_16x16x32_bf16 v[0:3], v[166:169], v[210:213], v[0:3]
	v_mfma_f32_16x16x32_bf16 v[56:59], v[162:165], v[182:185], v[56:59]
	v_mfma_f32_16x16x32_bf16 v[52:55], v[174:177], v[182:185], v[52:55]
	v_mfma_f32_16x16x32_bf16 v[40:43], v[162:165], v[190:193], v[40:43]
	v_mfma_f32_16x16x32_bf16 v[36:39], v[174:177], v[190:193], v[36:39]
	v_mfma_f32_16x16x32_bf16 v[20:23], v[162:165], v[206:209], v[20:23]
	v_mfma_f32_16x16x32_bf16 v[16:19], v[174:177], v[206:209], v[16:19]
	v_mfma_f32_16x16x32_bf16 v[4:7], v[162:165], v[214:217], v[4:7]
	v_mfma_f32_16x16x32_bf16 v[0:3], v[174:177], v[214:217], v[0:3]
	s_setprio 0
	s_barrier
	s_add_i32 s59, s59, 2
	s_add_u32 s0, s0, 0x100
	s_addc_u32 s1, s1, 0
	s_add_u32 s47, s47, 0x100
	s_addc_u32 s58, s58, 0
	s_cmp_gt_u32 s59, 13
	s_branch .LBB0_342
